# v17 + P6 walks its row-tile groups in reverse of P5's write order (memory-side cache reuse of U)
# speedup vs baseline: 1.0600x; 1.0052x over previous
.LBB0_830:
	s_cmp_lt_i32 s86, 7
	s_cselect_b64 s[0:1], -1, 0
	s_add_u32 s8, s46, 0x2000000
	s_addc_u32 s9, s47, 0
	s_and_b64 s[10:11], s[0:1], s[2:3]
	s_andn2_b64 vcc, exec, s[10:11]
	s_cbranch_vccnz .LBB0_865
	s_cmpk_lt_i32 s76, 0x600
	s_cselect_b64 s[2:3], -1, 0
	s_cmpk_gt_i32 s76, 0x5ff
	v_readfirstlane_b32 s4, v161
	s_cbranch_scc1 .LBB0_833
	s_ashr_i32 s0, s76, 31
	s_lshr_b32 s0, s0, 29
	s_add_i32 s0, s76, s0
	s_ashr_i32 s1, s0, 3
	s_and_b32 s0, s0, -8
	s_sub_i32 s0, s76, s0
	s_cmp_lt_i32 s0, 0
	s_movk_i32 s5, 0xc1
	s_cselect_b32 s5, s5, 0xc0
	s_mul_i32 s0, s0, s5
	s_add_i32 s0, s0, s1
	s_ashr_i32 s1, s0, 31
	s_lshr_b32 s1, s1, 27
	s_add_i32 s1, s0, s1
	s_ashr_i32 s5, s1, 5
	s_and_b32 s1, s1, 0xffe0
	s_sub_i32 s0, s0, s1
	s_bfe_i32 s1, s0, 0x80000
	s_bfe_u32 s1, s1, 0x3000c
	s_add_i32 s1, s0, s1
	s_bfe_i32 s12, s1, 0x80000
	s_and_b32 s1, s1, 0xf8
	s_sub_i32 s0, s0, s1
	s_lshl_b32 s5, s5, 3
	s_sext_i32_i16 s13, s12
	s_sext_i32_i8 s0, s0
	s_add_i32 s12, s5, s0
	s_ashr_i32 s34, s13, 3
	s_and_b32 s98, s76, 7
	s_mul_i32 s98, s98, 12
	s_add_i32 s98, s98, 5
	s_lshr_b32 s99, s12, 3
	s_sub_i32 s98, s98, s99
	s_and_b32 s12, s12, 7
	s_lshl3_add_u32 s12, s98, s12

.LBB0_839:
	s_add_i32 s51, s51, 1
	s_mul_i32 s4, s51, s42
	s_mul_hi_u32 s5, s51, s85
	s_add_i32 s5, s5, s4
	s_mul_i32 s4, s51, s85
	s_add_u32 s26, s4, s76
	s_addc_u32 s27, s5, s43
	v_cmp_gt_i64_e32 vcc, s[26:27], v[142:143]
	v_cmp_lt_i64_e64 s[4:5], s[26:27], v[140:141]
	s_cbranch_vccnz .LBB0_841
	s_ashr_i32 s24, s26, 31
	s_lshr_b32 s24, s24, 29
	s_add_i32 s24, s26, s24
	s_ashr_i32 s25, s24, 3
	s_and_b32 s24, s24, -8
	s_sub_i32 s24, s26, s24
	s_cmp_lt_i32 s24, 0
	s_cselect_b32 s26, s48, 0xc0
	s_mul_i32 s24, s24, s26
	s_add_i32 s24, s24, s25
	s_ashr_i32 s25, s24, 31
	s_lshr_b32 s25, s25, 27
	s_add_i32 s25, s24, s25
	s_ashr_i32 s26, s25, 5
	s_lshl_b32 s26, s26, 3
	s_sub_i32 s27, 0x180, s26
	s_min_i32 s27, s27, 8
	s_abs_i32 s28, s27
	v_cvt_f32_u32_e32 v0, s28
	s_sub_i32 s38, 0, s28
	s_andn2_b32 s25, s25, 31
	s_sub_i32 s24, s24, s25
	v_rcp_iflag_f32_e32 v0, v0
	s_abs_i32 s25, s24
	s_xor_b32 s29, s24, s27
	s_ashr_i32 s29, s29, 31
	v_mul_f32_e32 v0, 0x4f7ffffe, v0
	v_cvt_u32_f32_e32 v0, v0
	s_nop 0
	v_readfirstlane_b32 s39, v0
	s_mul_i32 s38, s38, s39
	s_mul_hi_u32 s38, s39, s38
	s_add_i32 s39, s39, s38
	s_mul_hi_u32 s38, s25, s39
	s_mul_i32 s39, s38, s28
	s_sub_i32 s25, s25, s39
	s_add_i32 s52, s38, 1
	s_sub_i32 s39, s25, s28
	s_cmp_ge_u32 s25, s28
	s_cselect_b32 s38, s52, s38
	s_cselect_b32 s25, s39, s25
	s_add_i32 s39, s38, 1
	s_cmp_ge_u32 s25, s28
	s_cselect_b32 s25, s39, s38
	s_xor_b32 s25, s25, s29
	s_sub_i32 s52, s25, s29
	s_mul_i32 s25, s52, s27
	s_sub_i32 s24, s24, s25
	s_add_i32 s24, s26, s24
	s_and_b32 s98, s76, 7
	s_mul_i32 s98, s98, 12
	s_add_i32 s98, s98, 5
	s_lshr_b32 s99, s24, 3
	s_sub_i32 s98, s98, s99
	s_and_b32 s24, s24, 7
	s_lshl3_add_u32 s24, s98, s24
